# attention key-block loop: the four divergent lane-group diamonds (exec save/restore + branches, all paths executed) replaced by mask selects and multiplies; on top of previous best
# speedup vs baseline: 1.0168x; 1.0168x over previous
; __device__ __forceinline__ void attn_unit(Frame& F, int b, int h, int qt, int kb_lo, int nkb, const bf16* QB, const bf16* KB, const bf16* VT, bf16* OUT, float bias2, f32x4* part, float* tpart) {
;     ...
;             for (int st = 0; st < 4; ++st) {
;                 const float sp2 = om[st][3], sp1 = sp2 * om[st][2], sp0 = sp1 * om[st][1]; lt[st] = sp0 * om[st][0];
;                 bt[st][2] *= sp2; bt[st][1] *= sp1; bt[st][0] *= sp0;
;                 const float xa = __shfl_xor(lt[st], 16), xb = __shfl_xor(lt[st], 32), xc = __shfl_xor(lt[st], 48);
;                 X[st] = (g == 0) ? xa * xb * xc : (g == 1) ? xb * xc : (g == 2) ? xa : 1.f;
;                 GT[st] = lt[st] * xa * xb * xc;
;             }
.LBB0_1065:
	s_or_b64 exec, exec, s[4:5]
	v_and_b32_e32 v111, 64, v218
	v_xor_b32_e32 v110, 16, v218
	v_add_u32_e32 v111, 64, v111
	v_cmp_lt_i32_e64 s[4:5], v110, v111
	s_nop 1
	v_cndmask_b32_e64 v110, v218, v110, s[4:5]
	v_lshlrev_b32_e32 v135, 2, v110
	v_xor_b32_e32 v110, 32, v218
	v_cmp_lt_i32_e64 s[4:5], v110, v111
	s_nop 1
	v_cndmask_b32_e64 v110, v218, v110, s[4:5]
	v_lshlrev_b32_e32 v136, 2, v110
	v_xor_b32_e32 v110, 48, v218
	v_cmp_lt_i32_e64 s[4:5], v110, v111
	v_mul_f32_e32 v111, v127, v134
	s_nop 0
	v_cndmask_b32_e64 v110, v218, v110, s[4:5]
	v_lshlrev_b32_e32 v137, 2, v110
	v_mul_f32_e32 v110, v111, v109
	v_mul_f32_e32 v112, v110, v108
	ds_bpermute_b32 v113, v135, v112
	ds_bpermute_b32 v114, v136, v112
	ds_bpermute_b32 v115, v137, v112
	s_orn2_b64 s[6:7], vcc, s[0:1]
	s_nand_b64 s[16:17], s[0:1], s[38:39]
	s_waitcnt lgkmcnt(0)
	v_mul_f32_e32 v108, v114, v115
	v_cndmask_b32_e64 v116, 1.0, v113, s[6:7]
	v_cndmask_b32_e64 v108, 1.0, v108, s[16:17]
	v_mul_f32_e32 v116, v116, v108
	v_mul_f32_e32 v109, v128, v133
	v_mul_f32_e32 v108, v109, v107
	v_mul_f32_e32 v133, v108, v106
	ds_bpermute_b32 v134, v135, v133
	ds_bpermute_b32 v138, v136, v133
	ds_bpermute_b32 v139, v137, v133
	s_waitcnt lgkmcnt(0)
	v_mul_f32_e32 v106, v138, v139
	v_cndmask_b32_e64 v117, 1.0, v134, s[6:7]
	v_cndmask_b32_e64 v106, 1.0, v106, s[16:17]
	v_mul_f32_e32 v117, v117, v106
	v_mul_f32_e32 v107, v129, v132
	v_mul_f32_e32 v106, v107, v105
	v_mul_f32_e32 v140, v106, v104
	ds_bpermute_b32 v141, v135, v140
	ds_bpermute_b32 v142, v136, v140
	ds_bpermute_b32 v143, v137, v140
	s_waitcnt lgkmcnt(0)
	v_mul_f32_e32 v104, v142, v143
	v_cndmask_b32_e64 v132, 1.0, v141, s[6:7]
	v_cndmask_b32_e64 v104, 1.0, v104, s[16:17]
	v_mul_f32_e32 v132, v132, v104
	v_mul_f32_e32 v105, v130, v131
	v_mul_f32_e32 v104, v105, v103
	v_mul_f32_e32 v102, v104, v102
	ds_bpermute_b32 v131, v135, v102
	ds_bpermute_b32 v135, v136, v102
	ds_bpermute_b32 v136, v137, v102
	s_waitcnt lgkmcnt(0)
	v_mul_f32_e32 v104, v135, v136
	v_cndmask_b32_e64 v103, 1.0, v131, s[6:7]
	v_cndmask_b32_e64 v104, 1.0, v104, s[16:17]
	v_mul_f32_e32 v103, v103, v104
	s_mov_b64 s[4:5], exec
	s_branch .LBB0_1058
